# strategy 7 (instruction selection): attention fast path softmax row-sum accumulates exp pairs with v_pk_add_f32 into a 2-lane accumulator (80 v_add_f32 -> 40 packed adds + 1 final add per chunk); summ
# baseline (speedup 1.0000x reference)
; __device__ __forceinline__ void attn_phase(int wave_s, LAS unsigned char* lds, const bf16* QKV, bf16* O, const float* qg, const float* kg, const float* sinks, const float* bt) {
;     ...
;             { float s = 0.f;
; #pragma unroll
;                 for (int d0 = 0; d0 < 4; ++d0) {
;                     const float f0 = bflo(qw[d0].x), f1 = bfhi(qw[d0].x), f2 = bflo(qw[d0].y), f3 = bfhi(qw[d0].y), f4 = bflo(qw[d0].z), f5 = bfhi(qw[d0].z), f6 = bflo(qw[d0].w), f7 = bfhi(qw[d0].w);
;                     s += (f0 * f0 + f1 * f1) + (f2 * f2 + f3 * f3) + (f4 * f4 + f5 * f5) + (f6 * f6 + f7 * f7); }
;                 s = sum_x32(s);
;                 const float rs = __builtin_amdgcn_rsqf(s * (1.0f / 64.0f) + EPS) * (0.125f * LOG2E);
; #pragma unroll
;                 for (int d0 = 0; d0 < 4; ++d0) { const f32x4 g0 = *(const f32x4*)(qg + d0 * 16 + hi * 8), g1 = *(const f32x4*)(qg + d0 * 16 + hi * 8 + 4);
;                     v4u o; o.x = pk2(bflo(qw[d0].x) * rs * g0.x, bfhi(qw[d0].x) * rs * g0.y); o.y = pk2(bflo(qw[d0].y) * rs * g0.z, bfhi(qw[d0].y) * rs * g0.w);
;                     o.z = pk2(bflo(qw[d0].z) * rs * g1.x, bfhi(qw[d0].z) * rs * g1.y); o.w = pk2(bflo(qw[d0].w) * rs * g1.z, bfhi(qw[d0].w) * rs * g1.w);
;                     qr[d0] = __builtin_bit_cast(bf16x8, o); } }
;             if (c < 3) {
; #pragma unroll
;                 for (int d0 = 0; d0 < 4; ++d0) qw[d0] = *(const v4u*)(Qb + (size_t)(32 * (c + 1)) * NQKV + d0 * 16); }
;             f32x16 p[5]; float l = 0.f;
; #pragma unroll
;             for (int kk = 0; kk < 5; ++kk) { const bool blk_ok = (nb > 0) || (c + kk >= 4);
;                 if (blk_ok) {
; #pragma unroll
;                     for (int r = 0; r < 16; ++r) p[kk][r] = Bh[160 - 32 * kk - (r & 3) - 8 * (r >> 2)];
; #pragma unroll
;                     for (int d0 = 0; d0 < 4; ++d0) { const bf16x8 kf = *(const LAS bf16x8*)(Ks + ((c + kk) * 32 + r32) * KS_STRIDE + d0 * 16 + hi * 8);
;                         p[kk] = __builtin_amdgcn_mfma_f32_32x32x16_bf16(kf, qr[d0], p[kk], 0, 0, 0); }
;                 } else p[kk] = (f32x16){}; }
; #pragma unroll
;             for (int kk = 0; kk < 5; ++kk) { const bool blk_ok = (nb > 0) || (c + kk >= 4);
;                 if (blk_ok) {
; #pragma unroll
;                     for (int r = 0; r < 16; ++r) { const float e = __builtin_amdgcn_exp2f(p[kk][r]); p[kk][r] = e; l += e; } } }
.Lfa_q:
	v_mov_b32_e32 v37, v1
	v_add_f32_e32 v1, v58, v60
	v_fmamk_f32 v1, v1, 0x3c800000, v250
	v_rsq_f32_e32 v1, v1
	v_mov_b32_e32 v73, v77
	v_mov_b32_e32 v45, v61
	v_mov_b32_e32 v57, v67
	v_mul_f32_e32 v58, 0x3e38aa3b, v1
	v_pk_mul_f32 v[60:61], v[58:59], v[72:73] op_sel_hi:[0,1]
	v_mov_b32_e32 v67, v75
	v_pk_mul_f32 v[30:31], v[168:169], v[60:61]
	v_mov_b32_e32 v51, v53
	v_cvt_pk_bf16_f32 v112, v30, v31
	v_pk_mul_f32 v[30:31], v[58:59], v[66:67] op_sel_hi:[0,1]
	v_mov_b32_e32 v53, v55
	v_mov_b32_e32 v55, v65
	v_mov_b32_e32 v65, v69
	v_pk_mul_f32 v[30:31], v[170:171], v[30:31]
	v_mov_b32_e32 v63, v71
	v_cvt_pk_bf16_f32 v113, v30, v31
	v_pk_mul_f32 v[30:31], v[58:59], v[64:65] op_sel_hi:[0,1]
	v_pk_mul_f32 v[26:27], v[164:165], v[30:31]
	v_mov_b32_e32 v41, v43
	v_cvt_pk_bf16_f32 v114, v26, v27
	v_pk_mul_f32 v[26:27], v[58:59], v[62:63] op_sel_hi:[0,1]
	v_pk_mul_f32 v[26:27], v[166:167], v[26:27]
	v_mov_b32_e32 v43, v59
	v_cvt_pk_bf16_f32 v115, v26, v27
	v_pk_mul_f32 v[26:27], v[58:59], v[56:57] op_sel_hi:[0,1]
	v_pk_mul_f32 v[22:23], v[176:177], v[26:27]
	v_cndmask_b32_e64 v1, 0, 1, s[88:89]
	v_cvt_pk_bf16_f32 v116, v22, v23
	v_pk_mul_f32 v[22:23], v[58:59], v[54:55] op_sel_hi:[0,1]
	v_pk_mul_f32 v[22:23], v[178:179], v[22:23]
	v_cmp_ne_u32_e64 s[6:7], 1, v1
	v_cvt_pk_bf16_f32 v117, v22, v23
	v_pk_mul_f32 v[22:23], v[58:59], v[52:53] op_sel_hi:[0,1]
	v_pk_mul_f32 v[18:19], v[172:173], v[22:23]
	s_andn2_b64 vcc, exec, s[88:89]
	v_cvt_pk_bf16_f32 v118, v18, v19
	v_pk_mul_f32 v[18:19], v[58:59], v[50:51] op_sel_hi:[0,1]
	v_pk_mul_f32 v[18:19], v[174:175], v[18:19]
	s_nop 0
	v_cvt_pk_bf16_f32 v119, v18, v19
	v_pk_mul_f32 v[18:19], v[58:59], v[48:49] op_sel_hi:[0,1]
	v_pk_mul_f32 v[14:15], v[184:185], v[18:19]
	s_nop 0
	v_cvt_pk_bf16_f32 v120, v14, v15
	v_pk_mul_f32 v[14:15], v[58:59], v[46:47] op_sel_hi:[0,1]
	v_pk_mul_f32 v[14:15], v[186:187], v[14:15]
	s_nop 0
	v_cvt_pk_bf16_f32 v121, v14, v15
	v_pk_mul_f32 v[14:15], v[58:59], v[44:45] op_sel_hi:[0,1]
	v_pk_mul_f32 v[10:11], v[180:181], v[14:15]
	s_nop 0
	v_cvt_pk_bf16_f32 v122, v10, v11
	v_pk_mul_f32 v[10:11], v[58:59], v[42:43] op_sel_hi:[0,1]
	v_pk_mul_f32 v[10:11], v[182:183], v[10:11]
	s_nop 0
	v_cvt_pk_bf16_f32 v123, v10, v11
	v_pk_mul_f32 v[10:11], v[58:59], v[40:41] op_sel_hi:[0,1]
	v_pk_mul_f32 v[6:7], v[10:11], v[192:193]
	s_nop 0
	v_cvt_pk_bf16_f32 v124, v6, v7
	v_pk_mul_f32 v[6:7], v[58:59], v[38:39] op_sel_hi:[0,1]
	v_pk_mul_f32 v[6:7], v[6:7], v[194:195]
	s_nop 0
	v_cvt_pk_bf16_f32 v125, v6, v7
	v_pk_mul_f32 v[6:7], v[58:59], v[36:37] op_sel_hi:[0,1]
	v_pk_mul_f32 v[2:3], v[6:7], v[188:189]
	s_nop 0
	v_cvt_pk_bf16_f32 v126, v2, v3
	v_pk_mul_f32 v[2:3], v[58:59], v[34:35] op_sel_hi:[0,1]
	v_pk_mul_f32 v[2:3], v[2:3], v[190:191]
	s_nop 0
	v_cvt_pk_bf16_f32 v127, v2, v3
	s_waitcnt lgkmcnt(0)
	ds_read2_b32 v[16:17], v145 offset0:160 offset1:159
	ds_read2_b32 v[18:19], v145 offset0:158 offset1:157
	ds_read2_b32 v[20:21], v145 offset0:152 offset1:151
	ds_read2_b32 v[22:23], v145 offset0:150 offset1:149
	ds_read2_b32 v[24:25], v145 offset0:144 offset1:143
	ds_read2_b32 v[26:27], v145 offset0:142 offset1:141
	ds_read2_b32 v[28:29], v145 offset0:136 offset1:135
	ds_read2_b32 v[30:31], v145 offset0:134 offset1:133
	ds_read_b128 v[196:199], v157
	ds_read_b128 v[200:203], v157 offset:32
	ds_read_b128 v[204:207], v157 offset:64
	ds_read_b128 v[208:211], v157 offset:96
	v_mfma_f32_32x32x16_bf16 v[80:95], v[212:215], v[112:115], v[80:95]
	v_mfma_f32_32x32x16_bf16 v[80:95], v[216:219], v[116:119], v[80:95]
	v_mfma_f32_32x32x16_bf16 v[80:95], v[220:223], v[120:123], v[80:95]
	v_mfma_f32_32x32x16_bf16 v[80:95], v[224:227], v[124:127], v[80:95]
	s_waitcnt lgkmcnt(0)
	ds_read2_b32 v[32:33], v145 offset0:128 offset1:127
	ds_read2_b32 v[34:35], v145 offset0:126 offset1:125
	ds_read2_b32 v[36:37], v145 offset0:120 offset1:119
	ds_read2_b32 v[38:39], v145 offset0:118 offset1:117
	ds_read2_b32 v[40:41], v145 offset0:112 offset1:111
	ds_read2_b32 v[42:43], v145 offset0:110 offset1:109
	ds_read2_b32 v[44:45], v145 offset0:104 offset1:103
	ds_read2_b32 v[46:47], v145 offset0:102 offset1:101
	ds_read_b128 v[212:215], v157 offset:4608
	ds_read_b128 v[216:219], v157 offset:4640
	ds_read_b128 v[220:223], v157 offset:4672
	ds_read_b128 v[224:227], v157 offset:4704
	v_mfma_f32_32x32x16_bf16 v[16:31], v[196:199], v[112:115], v[16:31]
	v_mfma_f32_32x32x16_bf16 v[16:31], v[200:203], v[116:119], v[16:31]
	v_mfma_f32_32x32x16_bf16 v[16:31], v[204:207], v[120:123], v[16:31]
	v_mfma_f32_32x32x16_bf16 v[16:31], v[208:211], v[124:127], v[16:31]
	v_exp_f32_e32 v80, v80
	v_exp_f32_e32 v81, v81
	v_exp_f32_e32 v82, v82
	v_exp_f32_e32 v83, v83
	v_mov_b64_e32 v[246:247], v[80:81]
	v_exp_f32_e32 v84, v84
	v_exp_f32_e32 v85, v85
	v_pk_add_f32 v[246:247], v[82:83], v[246:247]
	v_exp_f32_e32 v86, v86
	v_exp_f32_e32 v87, v87
	v_pk_add_f32 v[246:247], v[84:85], v[246:247]
	v_exp_f32_e32 v88, v88
	v_exp_f32_e32 v89, v89
	v_pk_add_f32 v[246:247], v[86:87], v[246:247]
	v_exp_f32_e32 v90, v90
	v_exp_f32_e32 v91, v91
	v_pk_add_f32 v[246:247], v[88:89], v[246:247]
	v_exp_f32_e32 v92, v92
	v_exp_f32_e32 v93, v93
	v_pk_add_f32 v[246:247], v[90:91], v[246:247]
	v_exp_f32_e32 v94, v94
	v_exp_f32_e32 v95, v95
	v_pk_add_f32 v[246:247], v[92:93], v[246:247]
	v_pk_add_f32 v[246:247], v[94:95], v[246:247]
	s_waitcnt lgkmcnt(0)
; __device__ __forceinline__ float sum_x32(float t) { float a = t, b = t; asm volatile("s_nop 1\n\tv_permlane32_swap_b32 %0, %1" : "+v"(a), "+v"(b)); return a + b; }
; #define LAS __attribute__((address_space(3)))
; __device__ __forceinline__ void attn_phase(int wave_s, LAS unsigned char* lds, const bf16* QKV, bf16* O, const float* qg, const float* kg, const float* sinks, const float* bt) {
;     ...
;             for (int kk = 0; kk < 5; ++kk) { const bool blk_ok = (nb > 0) || (c + kk >= 4);
;                 if (blk_ok) {
; #pragma unroll
;                     for (int r = 0; r < 16; ++r) p[kk][r] = Bh[160 - 32 * kk - (r & 3) - 8 * (r >> 2)];
; #pragma unroll
;                     for (int d0 = 0; d0 < 4; ++d0) { const bf16x8 kf = *(const LAS bf16x8*)(Ks + ((c + kk) * 32 + r32) * KS_STRIDE + d0 * 16 + hi * 8);
;                         p[kk] = __builtin_amdgcn_mfma_f32_32x32x16_bf16(kf, qr[d0], p[kk], 0, 0, 0); }
;                 } else p[kk] = (f32x16){}; }
; #pragma unroll
;             for (int kk = 0; kk < 5; ++kk) { const bool blk_ok = (nb > 0) || (c + kk >= 4);
;                 if (blk_ok) {
; #pragma unroll
;                     for (int r = 0; r < 16; ++r) { const float e = __builtin_amdgcn_exp2f(p[kk][r]); p[kk][r] = e; l += e; } } }
;             l = sum_x32(l); l += __builtin_amdgcn_exp2f(sink2);
;             if (hi == 0) wsf[r32] = __builtin_amdgcn_rcpf(l);
	ds_read2_b32 v[48:49], v145 offset0:96 offset1:95
	ds_read2_b32 v[50:51], v145 offset0:94 offset1:93
	ds_read2_b32 v[52:53], v145 offset0:88 offset1:87
	ds_read2_b32 v[54:55], v145 offset0:86 offset1:85
	ds_read2_b32 v[56:57], v145 offset0:80 offset1:79
	ds_read2_b32 v[58:59], v145 offset0:78 offset1:77
	ds_read2_b32 v[60:61], v145 offset0:72 offset1:71
	ds_read2_b32 v[62:63], v145 offset0:70 offset1:69
	ds_read_b128 v[196:199], v157 offset:9216
	ds_read_b128 v[200:203], v157 offset:9248
	ds_read_b128 v[204:207], v157 offset:9280
	ds_read_b128 v[208:211], v157 offset:9312
	v_mfma_f32_32x32x16_bf16 v[32:47], v[212:215], v[112:115], v[32:47]
	v_mfma_f32_32x32x16_bf16 v[32:47], v[216:219], v[116:119], v[32:47]
	v_mfma_f32_32x32x16_bf16 v[32:47], v[220:223], v[120:123], v[32:47]
	v_mfma_f32_32x32x16_bf16 v[32:47], v[224:227], v[124:127], v[32:47]
	v_exp_f32_e32 v16, v16
	v_exp_f32_e32 v17, v17
	v_exp_f32_e32 v18, v18
	v_exp_f32_e32 v19, v19
	v_pk_add_f32 v[246:247], v[16:17], v[246:247]
	v_exp_f32_e32 v20, v20
	v_exp_f32_e32 v21, v21
	v_pk_add_f32 v[246:247], v[18:19], v[246:247]
	v_exp_f32_e32 v22, v22
	v_exp_f32_e32 v23, v23
	v_pk_add_f32 v[246:247], v[20:21], v[246:247]
	v_exp_f32_e32 v24, v24
	v_exp_f32_e32 v25, v25
	v_pk_add_f32 v[246:247], v[22:23], v[246:247]
	v_exp_f32_e32 v26, v26
	v_exp_f32_e32 v27, v27
	v_pk_add_f32 v[246:247], v[24:25], v[246:247]
	v_exp_f32_e32 v28, v28
	v_exp_f32_e32 v29, v29
	v_pk_add_f32 v[246:247], v[26:27], v[246:247]
	v_exp_f32_e32 v30, v30
	v_exp_f32_e32 v31, v31
	v_pk_add_f32 v[246:247], v[28:29], v[246:247]
	v_pk_add_f32 v[246:247], v[30:31], v[246:247]
	s_waitcnt lgkmcnt(0)
	ds_read2_b32 v[64:65], v145 offset0:64 offset1:63
	ds_read2_b32 v[66:67], v145 offset0:62 offset1:61
	ds_read2_b32 v[68:69], v145 offset0:56 offset1:55
	ds_read2_b32 v[70:71], v145 offset0:54 offset1:53
	ds_read2_b32 v[72:73], v145 offset0:48 offset1:47
	ds_read2_b32 v[74:75], v145 offset0:46 offset1:45
	ds_read2_b32 v[76:77], v145 offset0:40 offset1:39
	ds_read2_b32 v[78:79], v145 offset0:38 offset1:37
	ds_read_b128 v[212:215], v157 offset:13824
	ds_read_b128 v[216:219], v157 offset:13856
	ds_read_b128 v[220:223], v157 offset:13888
	ds_read_b128 v[224:227], v157 offset:13920
	v_mfma_f32_32x32x16_bf16 v[48:63], v[196:199], v[112:115], v[48:63]
	v_mfma_f32_32x32x16_bf16 v[48:63], v[200:203], v[116:119], v[48:63]
	v_mfma_f32_32x32x16_bf16 v[48:63], v[204:207], v[120:123], v[48:63]
	v_mfma_f32_32x32x16_bf16 v[48:63], v[208:211], v[124:127], v[48:63]
	v_exp_f32_e32 v32, v32
	v_exp_f32_e32 v33, v33
	v_exp_f32_e32 v34, v34
	v_exp_f32_e32 v35, v35
	v_pk_add_f32 v[246:247], v[32:33], v[246:247]
	v_exp_f32_e32 v36, v36
	v_exp_f32_e32 v37, v37
	v_pk_add_f32 v[246:247], v[34:35], v[246:247]
	v_exp_f32_e32 v38, v38
	v_exp_f32_e32 v39, v39
	v_pk_add_f32 v[246:247], v[36:37], v[246:247]
	v_exp_f32_e32 v40, v40
	v_exp_f32_e32 v41, v41
	v_pk_add_f32 v[246:247], v[38:39], v[246:247]
	v_exp_f32_e32 v42, v42
	v_exp_f32_e32 v43, v43
	v_pk_add_f32 v[246:247], v[40:41], v[246:247]
	v_exp_f32_e32 v44, v44
	v_exp_f32_e32 v45, v45
	v_pk_add_f32 v[246:247], v[42:43], v[246:247]
	v_exp_f32_e32 v46, v46
	v_exp_f32_e32 v47, v47
	v_pk_add_f32 v[246:247], v[44:45], v[246:247]
	v_pk_add_f32 v[246:247], v[46:47], v[246:247]
	s_waitcnt lgkmcnt(0)
	ds_read2_b64 v[196:199], v156 offset1:2
	ds_read2_b64 v[200:203], v244 offset0:32 offset1:34
	ds_read2_b64 v[204:207], v156 offset0:4 offset1:6
	ds_read2_b64 v[208:211], v244 offset0:36 offset1:38
	v_mfma_f32_32x32x16_bf16 v[64:79], v[212:215], v[112:115], v[64:79]
	v_mfma_f32_32x32x16_bf16 v[64:79], v[216:219], v[116:119], v[64:79]
	v_mfma_f32_32x32x16_bf16 v[64:79], v[220:223], v[120:123], v[64:79]
	v_mfma_f32_32x32x16_bf16 v[64:79], v[224:227], v[124:127], v[64:79]
	ds_read2_b64 v[212:215], v156 offset0:8 offset1:10
	ds_read2_b64 v[216:219], v244 offset0:40 offset1:42
	ds_read2_b64 v[220:223], v156 offset0:12 offset1:14
	ds_read2_b64 v[224:227], v244 offset0:44 offset1:46
	v_exp_f32_e32 v48, v48
	v_exp_f32_e32 v49, v49
	v_exp_f32_e32 v50, v50
	v_exp_f32_e32 v51, v51
	v_pk_add_f32 v[246:247], v[48:49], v[246:247]
	v_exp_f32_e32 v52, v52
	v_exp_f32_e32 v53, v53
	v_pk_add_f32 v[246:247], v[50:51], v[246:247]
	v_exp_f32_e32 v54, v54
	v_exp_f32_e32 v55, v55
	v_pk_add_f32 v[246:247], v[52:53], v[246:247]
	v_exp_f32_e32 v56, v56
	v_exp_f32_e32 v57, v57
	v_pk_add_f32 v[246:247], v[54:55], v[246:247]
	v_exp_f32_e32 v58, v58
	v_exp_f32_e32 v59, v59
	v_pk_add_f32 v[246:247], v[56:57], v[246:247]
	v_exp_f32_e32 v60, v60
	v_exp_f32_e32 v61, v61
	v_pk_add_f32 v[246:247], v[58:59], v[246:247]
	v_exp_f32_e32 v62, v62
	v_exp_f32_e32 v63, v63
	v_pk_add_f32 v[246:247], v[60:61], v[246:247]
	v_pk_add_f32 v[246:247], v[62:63], v[246:247]
	v_exp_f32_e32 v64, v64
	v_exp_f32_e32 v65, v65
	v_exp_f32_e32 v66, v66
	v_exp_f32_e32 v67, v67
	v_pk_add_f32 v[246:247], v[64:65], v[246:247]
	v_exp_f32_e32 v68, v68
	v_exp_f32_e32 v69, v69
	v_pk_add_f32 v[246:247], v[66:67], v[246:247]
	v_exp_f32_e32 v70, v70
	v_exp_f32_e32 v71, v71
	v_pk_add_f32 v[246:247], v[68:69], v[246:247]
	v_exp_f32_e32 v72, v72
	v_exp_f32_e32 v73, v73
	v_pk_add_f32 v[246:247], v[70:71], v[246:247]
	v_exp_f32_e32 v74, v74
	v_exp_f32_e32 v75, v75
	v_pk_add_f32 v[246:247], v[72:73], v[246:247]
	v_exp_f32_e32 v76, v76
	v_exp_f32_e32 v77, v77
	v_pk_add_f32 v[246:247], v[74:75], v[246:247]
	v_exp_f32_e32 v78, v78
	v_exp_f32_e32 v79, v79
	v_pk_add_f32 v[246:247], v[76:77], v[246:247]
	v_pk_add_f32 v[246:247], v[78:79], v[246:247]
	v_add_f32_e32 v1, v246, v247
	v_mov_b32_e32 v2, v1
	s_nop 1
	v_permlane32_swap_b32 v2, v1
	s_and_saveexec_b64 s[2:3], s[4:5]
	s_cbranch_execz .Lfa_nod
	v_add_f32_e32 v1, v2, v1
	v_add_f32_e32 v1, v137, v1
	v_rcp_f32_e32 v1, v1
	ds_write_b32 v146, v1
